# v31 + prep maps epilogue: scalar base + per-lane offset + immediate row offsets for the 2-byte stores (no per-store 64-bit address VALU), k-map weights read from LDS up front
# speedup vs baseline: 1.0511x; 1.0030x over previous
; DI bf16_t f2bf(float f) { return (bf16_t)cvt_pk_bf16(f, 0.f); }
; DI int crow(int i, int hh) { return (i & 3) + 8 * (i >> 2) + 4 * hh; }
; DI void prep_phase(PARAMS P, int l, int g, LAS unsigned char* lds, int wave, int lane) {
;     ...
;                 const int e = hd * 128 + 32 * nb + r;
;                 if (mt == 1) {
;                     bf16_t* mk = gb + (size_t)CP_MK * G0ROWS; bf16_t* mks = gb + (size_t)CP_MKST * G0ROWS; float dn = 0.f;
; #pragma unroll
;                     for (int i = 0; i < 16; ++i) {
;                         int t0 = crow(i, hh); asm volatile("" : "+v"(t0)); const int t1 = 32 + t0; const float k0 = a0[i] * 0.08838834764831845f, k1 = a1[i] * 0.08838834764831845f;
;                         const float w0 = WSTl[hd * 64 + t0], w1 = WSTl[hd * 64 + t1];
;                         mk[(size_t)(row0 + t0) * 512 + e] = f2bf(k0); mk[(size_t)(row0 + t1) * 512 + e] = f2bf(k1);
;                         mks[(size_t)(row0 + t0) * 512 + e] = f2bf(k0 * w0); mks[(size_t)(row0 + t1) * 512 + e] = f2bf(k1 * w1);
;                         dn += k0 * w0 + k1 * w1;
;                     }
;                     dn += __shfl_xor(dn, 32);
;                     if (hh == 0) DN[(size_t)(cid * 4 + hd) * 128 + 32 * nb + r] = dn;
;                 } else {
;                     bf16_t* o = gb + (size_t)(mt == 0 ? CP_MQ : CP_MV) * G0ROWS;
; #pragma unroll
;                     for (int i = 0; i < 16; ++i) { int t0 = crow(i, hh); asm volatile("" : "+v"(t0)); o[(size_t)(row0 + t0) * 512 + e] = f2bf(a0[i]); o[(size_t)(row0 + 32 + t0) * 512 + e] = f2bf(a1[i]); }
.LBB0_748:
	s_cmp_lt_u32 s33, 16
	s_mov_b32 s4, 0x8c00000
	s_cselect_b32 s4, s4, 0xa640000
	s_add_u32 s4, s12, s4
	s_addc_u32 s5, s18, 0
	s_lshl_b32 s100, s6, 10
	s_add_u32 s4, s4, s100
	s_addc_u32 s5, s5, 0
	v_lshl_or_b32 v126, v94, 10, v32
	v_add_u32_e32 v127, 0x8000, v126
	s_nop 15
	v_cvt_pk_bf16_f32 v130, v0, s0
	v_cvt_pk_bf16_f32 v131, v16, s0
	global_store_short v126, v130, s[4:5]
	global_store_short v127, v131, s[4:5]
	v_cvt_pk_bf16_f32 v132, v1, s0
	v_cvt_pk_bf16_f32 v133, v17, s0
	global_store_short v126, v132, s[4:5] offset:1024
	global_store_short v127, v133, s[4:5] offset:1024
	v_cvt_pk_bf16_f32 v134, v2, s0
	v_cvt_pk_bf16_f32 v135, v18, s0
	global_store_short v126, v134, s[4:5] offset:2048
	global_store_short v127, v135, s[4:5] offset:2048
	v_cvt_pk_bf16_f32 v136, v3, s0
	v_cvt_pk_bf16_f32 v137, v19, s0
	global_store_short v126, v136, s[4:5] offset:3072
	global_store_short v127, v137, s[4:5] offset:3072
	s_add_u32 s4, s4, 0x2000
	s_addc_u32 s5, s5, 0
	v_cvt_pk_bf16_f32 v130, v4, s0
	v_cvt_pk_bf16_f32 v131, v20, s0
	global_store_short v126, v130, s[4:5]
	global_store_short v127, v131, s[4:5]
	v_cvt_pk_bf16_f32 v132, v5, s0
	v_cvt_pk_bf16_f32 v133, v21, s0
	global_store_short v126, v132, s[4:5] offset:1024
	global_store_short v127, v133, s[4:5] offset:1024
	v_cvt_pk_bf16_f32 v134, v6, s0
	v_cvt_pk_bf16_f32 v135, v22, s0
	global_store_short v126, v134, s[4:5] offset:2048
	global_store_short v127, v135, s[4:5] offset:2048
	v_cvt_pk_bf16_f32 v136, v7, s0
	v_cvt_pk_bf16_f32 v137, v23, s0
	global_store_short v126, v136, s[4:5] offset:3072
	global_store_short v127, v137, s[4:5] offset:3072
	s_add_u32 s4, s4, 0x2000
	s_addc_u32 s5, s5, 0
	v_cvt_pk_bf16_f32 v130, v8, s0
	v_cvt_pk_bf16_f32 v131, v24, s0
	global_store_short v126, v130, s[4:5]
	global_store_short v127, v131, s[4:5]
	v_cvt_pk_bf16_f32 v132, v9, s0
	v_cvt_pk_bf16_f32 v133, v25, s0
	global_store_short v126, v132, s[4:5] offset:1024
	global_store_short v127, v133, s[4:5] offset:1024
	v_cvt_pk_bf16_f32 v134, v10, s0
	v_cvt_pk_bf16_f32 v135, v26, s0
	global_store_short v126, v134, s[4:5] offset:2048
	global_store_short v127, v135, s[4:5] offset:2048
	v_cvt_pk_bf16_f32 v136, v11, s0
	v_cvt_pk_bf16_f32 v137, v27, s0
	global_store_short v126, v136, s[4:5] offset:3072
	global_store_short v127, v137, s[4:5] offset:3072
	s_add_u32 s4, s4, 0x2000
	s_addc_u32 s5, s5, 0
	v_cvt_pk_bf16_f32 v130, v12, s0
	v_cvt_pk_bf16_f32 v131, v28, s0
	global_store_short v126, v130, s[4:5]
	global_store_short v127, v131, s[4:5]
	v_cvt_pk_bf16_f32 v132, v13, s0
	v_cvt_pk_bf16_f32 v133, v29, s0
	global_store_short v126, v132, s[4:5] offset:1024
	global_store_short v127, v133, s[4:5] offset:1024
	v_cvt_pk_bf16_f32 v134, v14, s0
	v_cvt_pk_bf16_f32 v135, v30, s0
	global_store_short v126, v134, s[4:5] offset:2048
	global_store_short v127, v135, s[4:5] offset:2048
	v_cvt_pk_bf16_f32 v136, v15, s0
	v_cvt_pk_bf16_f32 v137, v31, s0
	global_store_short v126, v136, s[4:5] offset:3072
	global_store_short v127, v137, s[4:5] offset:3072
	s_branch .LBB0_745
.LBB0_749:
	s_add_i32 s4, s21, 0x22000
	v_lshl_add_u32 v128, v94, 2, s4
	v_lshl_or_b32 v126, v94, 10, v32
	v_add_u32_e32 v127, 0x8000, v126
	ds_read2_b32 v[164:165], v128 offset0:0 offset1:32
	ds_read2_b32 v[166:167], v128 offset0:1 offset1:33
	ds_read2_b32 v[168:169], v128 offset0:2 offset1:34
	ds_read2_b32 v[170:171], v128 offset0:3 offset1:35
	ds_read2_b32 v[172:173], v128 offset0:8 offset1:40
	ds_read2_b32 v[174:175], v128 offset0:9 offset1:41
	ds_read2_b32 v[176:177], v128 offset0:10 offset1:42
	ds_read2_b32 v[178:179], v128 offset0:11 offset1:43
	ds_read2_b32 v[180:181], v128 offset0:16 offset1:48
	ds_read2_b32 v[182:183], v128 offset0:17 offset1:49
	ds_read2_b32 v[184:185], v128 offset0:18 offset1:50
	ds_read2_b32 v[186:187], v128 offset0:19 offset1:51
	ds_read2_b32 v[188:189], v128 offset0:24 offset1:56
	ds_read2_b32 v[190:191], v128 offset0:25 offset1:57
	ds_read2_b32 v[192:193], v128 offset0:26 offset1:58
	ds_read2_b32 v[194:195], v128 offset0:27 offset1:59
	s_lshl_b32 s100, s6, 10
	s_add_u32 s98, s74, s100
	s_addc_u32 s99, s75, 0
	s_add_u32 s64, s78, s100
	s_addc_u32 s65, s79, 0
	s_nop 7
	s_waitcnt lgkmcnt(15)
	v_mul_f32_e32 v130, 0x3db504f3, v0
	v_mul_f32_e32 v131, 0x3db504f3, v16
	v_cvt_pk_bf16_f32 v132, v130, s0
	v_cvt_pk_bf16_f32 v133, v131, s0
	global_store_short v126, v132, s[98:99]
	global_store_short v127, v133, s[98:99]
	v_mul_f32_e32 v134, v130, v164
	v_mul_f32_e32 v135, v131, v165
	v_cvt_pk_bf16_f32 v136, v134, s0
	v_cvt_pk_bf16_f32 v137, v135, s0
	global_store_short v126, v136, s[64:65]
	global_store_short v127, v137, s[64:65]
	v_fmac_f32_e32 v135, v130, v164
	v_add_f32_e32 v162, 0, v135
	s_waitcnt lgkmcnt(14)
	v_mul_f32_e32 v138, 0x3db504f3, v1
	v_mul_f32_e32 v139, 0x3db504f3, v17
	v_cvt_pk_bf16_f32 v140, v138, s0
	v_cvt_pk_bf16_f32 v141, v139, s0
	global_store_short v126, v140, s[98:99] offset:1024
	global_store_short v127, v141, s[98:99] offset:1024
	v_mul_f32_e32 v142, v138, v166
	v_mul_f32_e32 v143, v139, v167
	v_cvt_pk_bf16_f32 v144, v142, s0
	v_cvt_pk_bf16_f32 v145, v143, s0
	global_store_short v126, v144, s[64:65] offset:1024
	global_store_short v127, v145, s[64:65] offset:1024
	v_fmac_f32_e32 v143, v138, v166
	v_add_f32_e32 v162, v162, v143
	s_waitcnt lgkmcnt(13)
	v_mul_f32_e32 v146, 0x3db504f3, v2
	v_mul_f32_e32 v147, 0x3db504f3, v18
	v_cvt_pk_bf16_f32 v148, v146, s0
	v_cvt_pk_bf16_f32 v149, v147, s0
	global_store_short v126, v148, s[98:99] offset:2048
	global_store_short v127, v149, s[98:99] offset:2048
	v_mul_f32_e32 v150, v146, v168
	v_mul_f32_e32 v151, v147, v169
	v_cvt_pk_bf16_f32 v152, v150, s0
	v_cvt_pk_bf16_f32 v153, v151, s0
	global_store_short v126, v152, s[64:65] offset:2048
	global_store_short v127, v153, s[64:65] offset:2048
	v_fmac_f32_e32 v151, v146, v168
	v_add_f32_e32 v162, v162, v151
	s_waitcnt lgkmcnt(12)
; DI bf16_t f2bf(float f) { return (bf16_t)cvt_pk_bf16(f, 0.f); }
; DI int crow(int i, int hh) { return (i & 3) + 8 * (i >> 2) + 4 * hh; }
; DI void prep_phase(PARAMS P, int l, int g, LAS unsigned char* lds, int wave, int lane) {
;     ...
;                     bf16_t* mk = gb + (size_t)CP_MK * G0ROWS; bf16_t* mks = gb + (size_t)CP_MKST * G0ROWS; float dn = 0.f;
; #pragma unroll
;                     for (int i = 0; i < 16; ++i) {
;                         int t0 = crow(i, hh); asm volatile("" : "+v"(t0)); const int t1 = 32 + t0; const float k0 = a0[i] * 0.08838834764831845f, k1 = a1[i] * 0.08838834764831845f;
;                         const float w0 = WSTl[hd * 64 + t0], w1 = WSTl[hd * 64 + t1];
;                         mk[(size_t)(row0 + t0) * 512 + e] = f2bf(k0); mk[(size_t)(row0 + t1) * 512 + e] = f2bf(k1);
;                         mks[(size_t)(row0 + t0) * 512 + e] = f2bf(k0 * w0); mks[(size_t)(row0 + t1) * 512 + e] = f2bf(k1 * w1);
;                         dn += k0 * w0 + k1 * w1;
;                     }
	v_mul_f32_e32 v154, 0x3db504f3, v3
	v_mul_f32_e32 v155, 0x3db504f3, v19
	v_cvt_pk_bf16_f32 v156, v154, s0
	v_cvt_pk_bf16_f32 v157, v155, s0
	global_store_short v126, v156, s[98:99] offset:3072
	global_store_short v127, v157, s[98:99] offset:3072
	v_mul_f32_e32 v158, v154, v170
	v_mul_f32_e32 v159, v155, v171
	v_cvt_pk_bf16_f32 v160, v158, s0
	v_cvt_pk_bf16_f32 v161, v159, s0
	global_store_short v126, v160, s[64:65] offset:3072
	global_store_short v127, v161, s[64:65] offset:3072
	v_fmac_f32_e32 v159, v154, v170
	v_add_f32_e32 v162, v162, v159
	s_add_u32 s98, s98, 0x2000
	s_addc_u32 s99, s99, 0
	s_add_u32 s64, s64, 0x2000
	s_addc_u32 s65, s65, 0
	s_waitcnt lgkmcnt(11)
	v_mul_f32_e32 v130, 0x3db504f3, v4
	v_mul_f32_e32 v131, 0x3db504f3, v20
	v_cvt_pk_bf16_f32 v132, v130, s0
	v_cvt_pk_bf16_f32 v133, v131, s0
	global_store_short v126, v132, s[98:99]
	global_store_short v127, v133, s[98:99]
	v_mul_f32_e32 v134, v130, v172
	v_mul_f32_e32 v135, v131, v173
	v_cvt_pk_bf16_f32 v136, v134, s0
	v_cvt_pk_bf16_f32 v137, v135, s0
	global_store_short v126, v136, s[64:65]
	global_store_short v127, v137, s[64:65]
	v_fmac_f32_e32 v135, v130, v172
	v_add_f32_e32 v162, v162, v135
	s_waitcnt lgkmcnt(10)
	v_mul_f32_e32 v138, 0x3db504f3, v5
	v_mul_f32_e32 v139, 0x3db504f3, v21
	v_cvt_pk_bf16_f32 v140, v138, s0
	v_cvt_pk_bf16_f32 v141, v139, s0
	global_store_short v126, v140, s[98:99] offset:1024
	global_store_short v127, v141, s[98:99] offset:1024
	v_mul_f32_e32 v142, v138, v174
	v_mul_f32_e32 v143, v139, v175
	v_cvt_pk_bf16_f32 v144, v142, s0
	v_cvt_pk_bf16_f32 v145, v143, s0
	global_store_short v126, v144, s[64:65] offset:1024
	global_store_short v127, v145, s[64:65] offset:1024
	v_fmac_f32_e32 v143, v138, v174
	v_add_f32_e32 v162, v162, v143
	s_waitcnt lgkmcnt(9)
	v_mul_f32_e32 v146, 0x3db504f3, v6
	v_mul_f32_e32 v147, 0x3db504f3, v22
	v_cvt_pk_bf16_f32 v148, v146, s0
	v_cvt_pk_bf16_f32 v149, v147, s0
	global_store_short v126, v148, s[98:99] offset:2048
	global_store_short v127, v149, s[98:99] offset:2048
	v_mul_f32_e32 v150, v146, v176
	v_mul_f32_e32 v151, v147, v177
	v_cvt_pk_bf16_f32 v152, v150, s0
	v_cvt_pk_bf16_f32 v153, v151, s0
	global_store_short v126, v152, s[64:65] offset:2048
	global_store_short v127, v153, s[64:65] offset:2048
	v_fmac_f32_e32 v151, v146, v176
	v_add_f32_e32 v162, v162, v151
	s_waitcnt lgkmcnt(8)
	v_mul_f32_e32 v154, 0x3db504f3, v7
	v_mul_f32_e32 v155, 0x3db504f3, v23
	v_cvt_pk_bf16_f32 v156, v154, s0
	v_cvt_pk_bf16_f32 v157, v155, s0
	global_store_short v126, v156, s[98:99] offset:3072
	global_store_short v127, v157, s[98:99] offset:3072
	v_mul_f32_e32 v158, v154, v178
	v_mul_f32_e32 v159, v155, v179
	v_cvt_pk_bf16_f32 v160, v158, s0
	v_cvt_pk_bf16_f32 v161, v159, s0
	global_store_short v126, v160, s[64:65] offset:3072
	global_store_short v127, v161, s[64:65] offset:3072
	v_fmac_f32_e32 v159, v154, v178
	v_add_f32_e32 v162, v162, v159
	s_add_u32 s98, s98, 0x2000
	s_addc_u32 s99, s99, 0
	s_add_u32 s64, s64, 0x2000
	s_addc_u32 s65, s65, 0
	s_waitcnt lgkmcnt(7)
	v_mul_f32_e32 v130, 0x3db504f3, v8
	v_mul_f32_e32 v131, 0x3db504f3, v24
	v_cvt_pk_bf16_f32 v132, v130, s0
	v_cvt_pk_bf16_f32 v133, v131, s0
	global_store_short v126, v132, s[98:99]
	global_store_short v127, v133, s[98:99]
	v_mul_f32_e32 v134, v130, v180
	v_mul_f32_e32 v135, v131, v181
	v_cvt_pk_bf16_f32 v136, v134, s0
	v_cvt_pk_bf16_f32 v137, v135, s0
	global_store_short v126, v136, s[64:65]
	global_store_short v127, v137, s[64:65]
	v_fmac_f32_e32 v135, v130, v180
	v_add_f32_e32 v162, v162, v135
	s_waitcnt lgkmcnt(6)
	v_mul_f32_e32 v138, 0x3db504f3, v9
	v_mul_f32_e32 v139, 0x3db504f3, v25
	v_cvt_pk_bf16_f32 v140, v138, s0
	v_cvt_pk_bf16_f32 v141, v139, s0
	global_store_short v126, v140, s[98:99] offset:1024
	global_store_short v127, v141, s[98:99] offset:1024
	v_mul_f32_e32 v142, v138, v182
	v_mul_f32_e32 v143, v139, v183
	v_cvt_pk_bf16_f32 v144, v142, s0
	v_cvt_pk_bf16_f32 v145, v143, s0
	global_store_short v126, v144, s[64:65] offset:1024
	global_store_short v127, v145, s[64:65] offset:1024
	v_fmac_f32_e32 v143, v138, v182
	v_add_f32_e32 v162, v162, v143
	s_waitcnt lgkmcnt(5)
; DI bf16_t f2bf(float f) { return (bf16_t)cvt_pk_bf16(f, 0.f); }
; DI int crow(int i, int hh) { return (i & 3) + 8 * (i >> 2) + 4 * hh; }
; DI void prep_phase(PARAMS P, int l, int g, LAS unsigned char* lds, int wave, int lane) {
;     ...
;                     bf16_t* mk = gb + (size_t)CP_MK * G0ROWS; bf16_t* mks = gb + (size_t)CP_MKST * G0ROWS; float dn = 0.f;
; #pragma unroll
;                     for (int i = 0; i < 16; ++i) {
;                         int t0 = crow(i, hh); asm volatile("" : "+v"(t0)); const int t1 = 32 + t0; const float k0 = a0[i] * 0.08838834764831845f, k1 = a1[i] * 0.08838834764831845f;
;                         const float w0 = WSTl[hd * 64 + t0], w1 = WSTl[hd * 64 + t1];
;                         mk[(size_t)(row0 + t0) * 512 + e] = f2bf(k0); mk[(size_t)(row0 + t1) * 512 + e] = f2bf(k1);
;                         mks[(size_t)(row0 + t0) * 512 + e] = f2bf(k0 * w0); mks[(size_t)(row0 + t1) * 512 + e] = f2bf(k1 * w1);
;                         dn += k0 * w0 + k1 * w1;
;                     }
;                     dn += __shfl_xor(dn, 32);
;                     if (hh == 0) DN[(size_t)(cid * 4 + hd) * 128 + 32 * nb + r] = dn;
	v_mul_f32_e32 v146, 0x3db504f3, v10
	v_mul_f32_e32 v147, 0x3db504f3, v26
	v_cvt_pk_bf16_f32 v148, v146, s0
	v_cvt_pk_bf16_f32 v149, v147, s0
	global_store_short v126, v148, s[98:99] offset:2048
	global_store_short v127, v149, s[98:99] offset:2048
	v_mul_f32_e32 v150, v146, v184
	v_mul_f32_e32 v151, v147, v185
	v_cvt_pk_bf16_f32 v152, v150, s0
	v_cvt_pk_bf16_f32 v153, v151, s0
	global_store_short v126, v152, s[64:65] offset:2048
	global_store_short v127, v153, s[64:65] offset:2048
	v_fmac_f32_e32 v151, v146, v184
	v_add_f32_e32 v162, v162, v151
	s_waitcnt lgkmcnt(4)
	v_mul_f32_e32 v154, 0x3db504f3, v11
	v_mul_f32_e32 v155, 0x3db504f3, v27
	v_cvt_pk_bf16_f32 v156, v154, s0
	v_cvt_pk_bf16_f32 v157, v155, s0
	global_store_short v126, v156, s[98:99] offset:3072
	global_store_short v127, v157, s[98:99] offset:3072
	v_mul_f32_e32 v158, v154, v186
	v_mul_f32_e32 v159, v155, v187
	v_cvt_pk_bf16_f32 v160, v158, s0
	v_cvt_pk_bf16_f32 v161, v159, s0
	global_store_short v126, v160, s[64:65] offset:3072
	global_store_short v127, v161, s[64:65] offset:3072
	v_fmac_f32_e32 v159, v154, v186
	v_add_f32_e32 v162, v162, v159
	s_add_u32 s98, s98, 0x2000
	s_addc_u32 s99, s99, 0
	s_add_u32 s64, s64, 0x2000
	s_addc_u32 s65, s65, 0
	s_waitcnt lgkmcnt(3)
	v_mul_f32_e32 v130, 0x3db504f3, v12
	v_mul_f32_e32 v131, 0x3db504f3, v28
	v_cvt_pk_bf16_f32 v132, v130, s0
	v_cvt_pk_bf16_f32 v133, v131, s0
	global_store_short v126, v132, s[98:99]
	global_store_short v127, v133, s[98:99]
	v_mul_f32_e32 v134, v130, v188
	v_mul_f32_e32 v135, v131, v189
	v_cvt_pk_bf16_f32 v136, v134, s0
	v_cvt_pk_bf16_f32 v137, v135, s0
	global_store_short v126, v136, s[64:65]
	global_store_short v127, v137, s[64:65]
	v_fmac_f32_e32 v135, v130, v188
	v_add_f32_e32 v162, v162, v135
	s_waitcnt lgkmcnt(2)
	v_mul_f32_e32 v138, 0x3db504f3, v13
	v_mul_f32_e32 v139, 0x3db504f3, v29
	v_cvt_pk_bf16_f32 v140, v138, s0
	v_cvt_pk_bf16_f32 v141, v139, s0
	global_store_short v126, v140, s[98:99] offset:1024
	global_store_short v127, v141, s[98:99] offset:1024
	v_mul_f32_e32 v142, v138, v190
	v_mul_f32_e32 v143, v139, v191
	v_cvt_pk_bf16_f32 v144, v142, s0
	v_cvt_pk_bf16_f32 v145, v143, s0
	global_store_short v126, v144, s[64:65] offset:1024
	global_store_short v127, v145, s[64:65] offset:1024
	v_fmac_f32_e32 v143, v138, v190
	v_add_f32_e32 v162, v162, v143
	s_waitcnt lgkmcnt(1)
	v_mul_f32_e32 v146, 0x3db504f3, v14
	v_mul_f32_e32 v147, 0x3db504f3, v30
	v_cvt_pk_bf16_f32 v148, v146, s0
	v_cvt_pk_bf16_f32 v149, v147, s0
	global_store_short v126, v148, s[98:99] offset:2048
	global_store_short v127, v149, s[98:99] offset:2048
	v_mul_f32_e32 v150, v146, v192
	v_mul_f32_e32 v151, v147, v193
	v_cvt_pk_bf16_f32 v152, v150, s0
	v_cvt_pk_bf16_f32 v153, v151, s0
	global_store_short v126, v152, s[64:65] offset:2048
	global_store_short v127, v153, s[64:65] offset:2048
	v_fmac_f32_e32 v151, v146, v192
	v_add_f32_e32 v162, v162, v151
	s_waitcnt lgkmcnt(0)
	v_mul_f32_e32 v154, 0x3db504f3, v15
	v_mul_f32_e32 v155, 0x3db504f3, v31
	v_cvt_pk_bf16_f32 v156, v154, s0
	v_cvt_pk_bf16_f32 v157, v155, s0
	global_store_short v126, v156, s[98:99] offset:3072
	global_store_short v127, v157, s[98:99] offset:3072
	v_mul_f32_e32 v158, v154, v194
	v_mul_f32_e32 v159, v155, v195
	v_cvt_pk_bf16_f32 v160, v158, s0
	v_cvt_pk_bf16_f32 v161, v159, s0
	global_store_short v126, v160, s[64:65] offset:3072
	global_store_short v127, v161, s[64:65] offset:3072
	v_fmac_f32_e32 v159, v154, v194
	v_add_f32_e32 v162, v162, v159
	v_and_b32_e32 v8, 64, v235
	v_xor_b32_e32 v1, 32, v235
	v_add_u32_e32 v8, 64, v8
	v_cmp_lt_i32_e32 vcc, v1, v8
	v_mov_b32_e32 v0, v162
	v_cndmask_b32_e32 v1, v235, v1, vcc
	v_lshlrev_b32_e32 v1, 2, v1
	ds_bpermute_b32 v1, v1, v0
	s_and_saveexec_b64 s[4:5], s[44:45]
	s_cbranch_execz .LBB0_744
	s_or_b32 s64, s17, s3
	s_ashr_i32 s65, s64, 31
	s_lshl_b64 s[64:65], s[64:65], 9
	s_add_u32 s17, s0, s64
	s_addc_u32 s21, s1, s65
	s_lshl_b32 s20, s20, 2
	s_add_u32 s20, s17, s20
	s_waitcnt lgkmcnt(0)
	v_add_f32_e32 v0, v0, v1
	s_addc_u32 s21, s21, 0
	global_store_dword v124, v0, s[20:21]
	s_branch .LBB0_744
